# attention compressed branch: V^T fragment prefetch issued right after the K-fragment wait (flies during head 0 QK+softmax)
# baseline (speedup 1.0000x reference)
; #define MFMA16(a, b, c) __builtin_amdgcn_mfma_f32_16x16x32_f16((a), (b), (c), 0, 0, 0)
; DI void attn_phase(const Params& p, const int layer, const int wid_s) {
;     ...
;       const h16* kcb = (const h16*)(p.ws + OFF_KC) + (size_t)bg * 128 * 64;
;       const h16* vcb = (const h16*)(p.ws + OFF_VCT) + (size_t)bg * 64 * 128;
;       half8 kc0[8], kc1[8];
; #pragma unroll
;       for (int nt = 0; nt < 8; ++nt) {
;         if (nt * 256 > t0 - 16) { kc0[nt] = (half8){0, 0, 0, 0, 0, 0, 0, 0}; kc1[nt] = kc0[nt]; }
;         else { kc0[nt] = *(const half8*)(kcb + (nt * 16 + fr) * 64 + fq * 8); kc1[nt] = *(const half8*)(kcb + (nt * 16 + fr) * 64 + 32 + fq * 8); }
;       }
; #pragma unroll
;       for (int hp = 0; hp < 2; ++hp) {
;         half8 qc[2];
; #pragma unroll
;         for (int ks = 0; ks < 2; ++ks) qc[ks] = hp ? q[1][ks] : q[0][ks];
;         const float gate_c = hp ? gate[1][0] : gate[0][0];
;         f32x4 s[8];
;         float mx = M_INIT;
; #pragma unroll
;         for (int nt = 0; nt < 8; ++nt) {
;           const bool tinv = nt * 256 > t0 - 16, tfar = nt * 256 + 399 <= t0;
;           if (tinv) { s[nt] = (f32x4){MASKV, MASKV, MASKV, MASKV}; }
;           else {
;             s[nt] = MFMA16(kc0[nt], qc[0], ((f32x4){0.f, 0.f, 0.f, 0.f}));
;             s[nt] = MFMA16(kc1[nt], qc[1], s[nt]);
;             if (!tfar) {
; #pragma unroll
;               for (int j = 0; j < 4; ++j) {
;                 const int dist = dbase - (nt * 256 + j * 16);
;                 const int ix = dist < 0 ? 0 : (dist > 128 ? 128 : dist);
;                 const float bv = tabh[hp * 132 + ix];
;                 const float sv = s[nt][j] + bv;
;                 s[nt][j] = dist >= 0 ? sv : MASKV;
;               }
;             }
;     ...
;             const half8 vf = *(const half8*)(vcb + ((st * 64) + dt * 16 + fr) * 32 + fq * 8);
.LBB0_213:
	s_mulk_i32 s38, 0x210
	s_movk_i32 s20, 0x31c5
	v_cndmask_b32_e64 v0, 0, 1, s[0:1]
	s_waitcnt vmcnt(0) lgkmcnt(0)
	v_lshl_add_u64 v[246:247], v[142:143], 0, s[10:11]
	v_lshlrev_b32_e32 v254, 1, v148
	v_add_co_u32_e32 v246, vcc, v246, v254
	s_nop 1
	v_addc_co_u32_e32 v247, vcc, 0, v247, vcc
	v_add_co_u32_e32 v246, vcc, 0x2000, v246
	s_nop 1
	v_addc_co_u32_e32 v247, vcc, 0, v247, vcc
	v_add_co_u32_e32 v254, vcc, 0x1000, v246
	s_nop 1
	v_addc_co_u32_e32 v255, vcc, 0, v247, vcc
	global_load_dwordx4 v[198:201], v[246:247], off offset:-4096
	global_load_dwordx4 v[202:205], v[246:247], off offset:-3072
	global_load_dwordx4 v[206:209], v[246:247], off offset:-2048
	global_load_dwordx4 v[210:213], v[246:247], off offset:-1024
	global_load_dwordx4 v[214:217], v[246:247], off
	global_load_dwordx4 v[218:221], v[246:247], off offset:1024
	global_load_dwordx4 v[222:225], v[246:247], off offset:2048
	global_load_dwordx4 v[226:229], v[246:247], off offset:3072
	global_load_dwordx4 v[230:233], v[254:255], off
	global_load_dwordx4 v[234:237], v[254:255], off offset:1024
	global_load_dwordx4 v[238:241], v[254:255], off offset:2048
	global_load_dwordx4 v[242:245], v[254:255], off offset:3072
	v_pk_mul_f16 v11, v9, s20 op_sel_hi:[1,0]
	v_pk_mul_f16 v10, v8, s20 op_sel_hi:[1,0]
	v_pk_mul_f16 v9, v7, s20 op_sel_hi:[1,0]
	v_pk_mul_f16 v8, v6, s20 op_sel_hi:[1,0]
	v_pk_mul_f16 v15, v15, s20 op_sel_hi:[1,0]
	v_pk_mul_f16 v14, v14, s20 op_sel_hi:[1,0]
	v_pk_mul_f16 v13, v13, s20 op_sel_hi:[1,0]
	v_pk_mul_f16 v12, v12, s20 op_sel_hi:[1,0]
	s_add_i32 s38, s38, 0
	v_subrev_u32_e32 v189, 31, v187
	v_cmp_ne_u32_e64 s[40:41], 1, v0
	s_andn2_b64 vcc, exec, s[0:1]
	v_lshlrev_b32_e32 v154, 6, v123
	s_cbranch_vccnz .LBB0_217
	v_mfma_f32_16x16x32_f16 v[88:91], v[84:87], v[8:11], 0
	s_cmpk_gt_u32 s51, 0x18e
	v_mfma_f32_16x16x32_f16 v[88:91], v[80:83], v[12:15], v[88:91]
	s_cbranch_scc1 .LBB0_216
	v_or_b32_e32 v0, 16, v154
	v_or_b32_e32 v6, 48, v154
	v_or_b32_e32 v7, 32, v154
	v_sub_u32_e32 v0, v189, v0
	v_sub_u32_e32 v5, v189, v154
	v_sub_u32_e32 v92, v189, v6
	v_sub_u32_e32 v93, v189, v7
	v_med3_i32 v2, v5, 0, v158
	v_med3_i32 v3, v0, 0, v158
	v_med3_i32 v6, v93, 0, v158
	v_med3_i32 v7, v92, 0, v158
	v_lshl_add_u32 v2, v2, 2, s38
	v_lshl_add_u32 v3, v3, 2, s38
	v_lshl_add_u32 v6, v6, 2, s38
	v_lshl_add_u32 v7, v7, 2, s38
	ds_read_b32 v2, v2
	ds_read_b32 v6, v6
	ds_read_b32 v7, v7
	ds_read_b32 v3, v3
	v_cmp_lt_i32_e32 vcc, -1, v92
	s_waitcnt lgkmcnt(1)
	v_pk_add_f32 v[6:7], v[90:91], v[6:7]
	s_nop 0
	v_cndmask_b32_e32 v91, v4, v7, vcc
	v_cmp_lt_i32_e32 vcc, -1, v93
	s_waitcnt lgkmcnt(0)
	v_pk_add_f32 v[2:3], v[88:89], v[2:3]
	v_cndmask_b32_e32 v90, v4, v6, vcc
	v_cmp_lt_i32_e32 vcc, -1, v0
	s_nop 1
	v_cndmask_b32_e32 v89, v4, v3, vcc
	v_cmp_lt_i32_e32 vcc, -1, v5
	s_nop 1
	v_cndmask_b32_e32 v88, v4, v2, vcc
